# packed up-GEMM epilogue with the exp / rcp instructions interleaved between the packed ops of neighbouring element pairs
# baseline (speedup 1.0000x reference)
.LBB0_1016:
	s_mov_b32 s100, 0xbfb8aa3b
	s_mov_b32 s101, 0xbfb8aa3b
	v_mov_b32_e32 v250, 1.0
	v_mov_b32_e32 v251, 1.0
	s_waitcnt vmcnt(0)
	v_pk_fma_f32 v[200:201], v[108:109], v[156:157], v[128:129]
	s_waitcnt lgkmcnt(4)
	s_nop 1
	v_fmac_f32_dpp v200, v108, v148 row_shr:1 row_mask:0xf bank_mask:0xf
	v_fmac_f32_dpp v200, v192, v148 row_shl:15 row_mask:0xf bank_mask:0xf
	v_fmac_f32_dpp v200, v108, v152 row_shl:1 row_mask:0xf bank_mask:0xf
	v_fmac_f32_dpp v200, v112, v152 row_shr:15 row_mask:0xf bank_mask:0xf
	v_fmac_f32_dpp v201, v109, v149 row_shr:1 row_mask:0xf bank_mask:0xf
	v_fmac_f32_dpp v201, v193, v149 row_shl:15 row_mask:0xf bank_mask:0xf
	v_fmac_f32_dpp v201, v109, v153 row_shl:1 row_mask:0xf bank_mask:0xf
	v_fmac_f32_dpp v201, v113, v153 row_shr:15 row_mask:0xf bank_mask:0xf
	v_pk_fma_f32 v[202:203], v[110:111], v[158:159], v[130:131]
	v_fmac_f32_dpp v202, v110, v150 row_shr:1 row_mask:0xf bank_mask:0xf
	v_fmac_f32_dpp v202, v194, v150 row_shl:15 row_mask:0xf bank_mask:0xf
	v_fmac_f32_dpp v202, v110, v154 row_shl:1 row_mask:0xf bank_mask:0xf
	v_fmac_f32_dpp v202, v114, v154 row_shr:15 row_mask:0xf bank_mask:0xf
	v_fmac_f32_dpp v203, v111, v151 row_shr:1 row_mask:0xf bank_mask:0xf
	v_fmac_f32_dpp v203, v195, v151 row_shl:15 row_mask:0xf bank_mask:0xf
	v_fmac_f32_dpp v203, v111, v155 row_shl:1 row_mask:0xf bank_mask:0xf
	v_fmac_f32_dpp v203, v115, v155 row_shr:15 row_mask:0xf bank_mask:0xf
	v_pk_fma_f32 v[204:205], v[104:105], v[144:145], v[120:121]
	s_waitcnt lgkmcnt(3)
	v_fmac_f32_dpp v204, v104, v136 row_shr:1 row_mask:0xf bank_mask:0xf
	v_fmac_f32_dpp v204, v188, v136 row_shl:15 row_mask:0xf bank_mask:0xf
	v_fmac_f32_dpp v204, v104, v140 row_shl:1 row_mask:0xf bank_mask:0xf
	v_fmac_f32_dpp v204, v100, v140 row_shr:15 row_mask:0xf bank_mask:0xf
	v_fmac_f32_dpp v205, v105, v137 row_shr:1 row_mask:0xf bank_mask:0xf
	v_fmac_f32_dpp v205, v189, v137 row_shl:15 row_mask:0xf bank_mask:0xf
	v_fmac_f32_dpp v205, v105, v141 row_shl:1 row_mask:0xf bank_mask:0xf
	v_fmac_f32_dpp v205, v101, v141 row_shr:15 row_mask:0xf bank_mask:0xf
	v_pk_fma_f32 v[206:207], v[106:107], v[146:147], v[122:123]
	v_fmac_f32_dpp v206, v106, v138 row_shr:1 row_mask:0xf bank_mask:0xf
	v_fmac_f32_dpp v206, v190, v138 row_shl:15 row_mask:0xf bank_mask:0xf
	v_fmac_f32_dpp v206, v106, v142 row_shl:1 row_mask:0xf bank_mask:0xf
	v_fmac_f32_dpp v206, v102, v142 row_shr:15 row_mask:0xf bank_mask:0xf
	v_fmac_f32_dpp v207, v107, v139 row_shr:1 row_mask:0xf bank_mask:0xf
	v_fmac_f32_dpp v207, v191, v139 row_shl:15 row_mask:0xf bank_mask:0xf
	v_fmac_f32_dpp v207, v107, v143 row_shl:1 row_mask:0xf bank_mask:0xf
	v_fmac_f32_dpp v207, v103, v143 row_shr:15 row_mask:0xf bank_mask:0xf
	v_pk_mul_f32 v[246:247], v[200:201], s[100:101]
	v_pk_mul_f32 v[248:249], v[202:203], s[100:101]
	v_exp_f32_e32 v246, v246
	v_exp_f32_e32 v247, v247
	v_pk_mul_f32 v[224:225], v[204:205], s[100:101]
	v_exp_f32_e32 v248, v248
	v_exp_f32_e32 v249, v249
	v_pk_mul_f32 v[228:229], v[206:207], s[100:101]
	v_exp_f32_e32 v224, v224
	v_exp_f32_e32 v225, v225
	v_pk_add_f32 v[246:247], v[246:247], v[250:251]
	v_exp_f32_e32 v228, v228
	v_exp_f32_e32 v229, v229
	v_pk_add_f32 v[248:249], v[248:249], v[250:251]
	v_rcp_f32_e32 v246, v246
	v_rcp_f32_e32 v247, v247
	v_pk_add_f32 v[224:225], v[224:225], v[250:251]
	v_rcp_f32_e32 v248, v248
	v_rcp_f32_e32 v249, v249
	v_pk_add_f32 v[228:229], v[228:229], v[250:251]
	v_rcp_f32_e32 v224, v224
	v_rcp_f32_e32 v225, v225
	v_pk_mul_f32 v[246:247], v[200:201], v[246:247]
	v_rcp_f32_e32 v228, v228
	v_rcp_f32_e32 v229, v229
	v_pk_mul_f32 v[248:249], v[202:203], v[248:249]
	v_pk_mul_f32 v[246:247], v[160:161], v[246:247]
	v_pk_mul_f32 v[224:225], v[204:205], v[224:225]
	v_pk_mul_f32 v[248:249], v[162:163], v[248:249]
	s_nop 0
	v_pk_mul_f32 v[228:229], v[206:207], v[228:229]
	v_pk_mul_f32 v[224:225], v[132:133], v[224:225]
	v_pk_mul_f32 v[228:229], v[134:135], v[228:229]
	v_lshl_add_u32 v240, s36, 8, v232
	v_cvt_pk_bf16_f32 v160, v246, v247
	v_cvt_pk_bf16_f32 v161, v248, v249
	v_cvt_pk_bf16_f32 v162, v224, v225
	v_mov_b64_e32 v[132:133], s[54:55]
	v_cvt_pk_bf16_f32 v163, v228, v229
	v_mad_i64_i32 v[188:189], s[4:5], v240, s79, v[132:133]
	v_lshlrev_b64 v[134:135], 1, v[222:223]
	v_lshl_add_u64 v[188:189], v[188:189], 0, v[134:135]
	global_store_dwordx4 v[188:189], v[160:163], off
	s_andn2_b64 vcc, exec, s[44:45]
	s_nop 0
	v_pk_fma_f32 v[200:201], v[112:113], v[156:157], v[128:129]
	v_fmac_f32_dpp v200, v112, v148 row_shr:1 row_mask:0xf bank_mask:0xf
	v_fmac_f32_dpp v200, v108, v148 row_shl:15 row_mask:0xf bank_mask:0xf
	v_fmac_f32_dpp v200, v112, v152 row_shl:1 row_mask:0xf bank_mask:0xf
	v_fmac_f32_dpp v200, v86, v152 row_shr:15 row_mask:0xf bank_mask:0xf
	v_fmac_f32_dpp v201, v113, v149 row_shr:1 row_mask:0xf bank_mask:0xf
	v_fmac_f32_dpp v201, v109, v149 row_shl:15 row_mask:0xf bank_mask:0xf
	v_fmac_f32_dpp v201, v113, v153 row_shl:1 row_mask:0xf bank_mask:0xf
	v_fmac_f32_dpp v201, v87, v153 row_shr:15 row_mask:0xf bank_mask:0xf
	v_pk_fma_f32 v[202:203], v[114:115], v[158:159], v[130:131]
	v_fmac_f32_dpp v202, v114, v150 row_shr:1 row_mask:0xf bank_mask:0xf
	v_fmac_f32_dpp v202, v110, v150 row_shl:15 row_mask:0xf bank_mask:0xf
	v_fmac_f32_dpp v202, v114, v154 row_shl:1 row_mask:0xf bank_mask:0xf
	v_fmac_f32_dpp v202, v88, v154 row_shr:15 row_mask:0xf bank_mask:0xf
	v_fmac_f32_dpp v203, v115, v151 row_shr:1 row_mask:0xf bank_mask:0xf
	v_fmac_f32_dpp v203, v111, v151 row_shl:15 row_mask:0xf bank_mask:0xf
	v_fmac_f32_dpp v203, v115, v155 row_shl:1 row_mask:0xf bank_mask:0xf
	v_fmac_f32_dpp v203, v89, v155 row_shr:15 row_mask:0xf bank_mask:0xf
	v_pk_fma_f32 v[204:205], v[100:101], v[144:145], v[120:121]
	v_fmac_f32_dpp v204, v100, v136 row_shr:1 row_mask:0xf bank_mask:0xf
	v_fmac_f32_dpp v204, v104, v136 row_shl:15 row_mask:0xf bank_mask:0xf
	v_fmac_f32_dpp v204, v100, v140 row_shl:1 row_mask:0xf bank_mask:0xf
	v_fmac_f32_dpp v204, v82, v140 row_shr:15 row_mask:0xf bank_mask:0xf
	v_fmac_f32_dpp v205, v101, v137 row_shr:1 row_mask:0xf bank_mask:0xf
	v_fmac_f32_dpp v205, v105, v137 row_shl:15 row_mask:0xf bank_mask:0xf
	v_fmac_f32_dpp v205, v101, v141 row_shl:1 row_mask:0xf bank_mask:0xf
	v_fmac_f32_dpp v205, v83, v141 row_shr:15 row_mask:0xf bank_mask:0xf
	v_pk_fma_f32 v[206:207], v[102:103], v[146:147], v[122:123]
	v_fmac_f32_dpp v206, v102, v138 row_shr:1 row_mask:0xf bank_mask:0xf
	v_fmac_f32_dpp v206, v106, v138 row_shl:15 row_mask:0xf bank_mask:0xf
	v_fmac_f32_dpp v206, v102, v142 row_shl:1 row_mask:0xf bank_mask:0xf
	v_fmac_f32_dpp v206, v84, v142 row_shr:15 row_mask:0xf bank_mask:0xf
	v_fmac_f32_dpp v207, v103, v139 row_shr:1 row_mask:0xf bank_mask:0xf
	v_fmac_f32_dpp v207, v107, v139 row_shl:15 row_mask:0xf bank_mask:0xf
	v_fmac_f32_dpp v207, v103, v143 row_shl:1 row_mask:0xf bank_mask:0xf
	v_fmac_f32_dpp v207, v85, v143 row_shr:15 row_mask:0xf bank_mask:0xf
	v_pk_mul_f32 v[246:247], v[200:201], s[100:101]
	v_pk_mul_f32 v[248:249], v[202:203], s[100:101]
	v_exp_f32_e32 v246, v246
	v_exp_f32_e32 v247, v247
	v_pk_mul_f32 v[224:225], v[204:205], s[100:101]
	v_exp_f32_e32 v248, v248
	v_exp_f32_e32 v249, v249
	v_pk_mul_f32 v[228:229], v[206:207], s[100:101]
	v_exp_f32_e32 v224, v224
	v_exp_f32_e32 v225, v225
	v_pk_add_f32 v[246:247], v[246:247], v[250:251]
	v_exp_f32_e32 v228, v228
	v_exp_f32_e32 v229, v229
	v_pk_add_f32 v[248:249], v[248:249], v[250:251]
	v_rcp_f32_e32 v246, v246
	v_rcp_f32_e32 v247, v247
	v_pk_add_f32 v[224:225], v[224:225], v[250:251]
	v_rcp_f32_e32 v248, v248
	v_rcp_f32_e32 v249, v249
	v_pk_add_f32 v[228:229], v[228:229], v[250:251]
	v_rcp_f32_e32 v224, v224
	v_rcp_f32_e32 v225, v225
	v_pk_mul_f32 v[246:247], v[200:201], v[246:247]
	v_rcp_f32_e32 v228, v228
	v_rcp_f32_e32 v229, v229
	v_pk_mul_f32 v[248:249], v[202:203], v[248:249]
	v_pk_mul_f32 v[246:247], v[124:125], v[246:247]
	v_pk_mul_f32 v[224:225], v[204:205], v[224:225]
	v_pk_mul_f32 v[248:249], v[126:127], v[248:249]
	s_nop 0
	v_pk_mul_f32 v[228:229], v[206:207], v[228:229]
	v_pk_mul_f32 v[224:225], v[116:117], v[224:225]
	v_pk_mul_f32 v[228:229], v[118:119], v[228:229]
	v_cvt_pk_bf16_f32 v104, v246, v247
	v_or_b32_e32 v108, 16, v240
	v_cvt_pk_bf16_f32 v105, v248, v249
	v_mad_i64_i32 v[108:109], s[4:5], v108, s79, v[132:133]
	v_lshl_add_u64 v[108:109], v[108:109], 0, v[134:135]
	v_cvt_pk_bf16_f32 v106, v224, v225
	v_cvt_pk_bf16_f32 v107, v228, v229
	global_store_dwordx4 v[108:109], v[104:107], off
	v_pk_fma_f32 v[204:205], v[82:83], v[144:145], v[120:121]
	v_fmac_f32_dpp v204, v82, v136 row_shr:1 row_mask:0xf bank_mask:0xf
	v_fmac_f32_dpp v204, v100, v136 row_shl:15 row_mask:0xf bank_mask:0xf
	v_fmac_f32_dpp v204, v82, v140 row_shl:1 row_mask:0xf bank_mask:0xf
	v_fmac_f32_dpp v204, v66, v140 row_shr:15 row_mask:0xf bank_mask:0xf
	v_fmac_f32_dpp v205, v83, v137 row_shr:1 row_mask:0xf bank_mask:0xf
	v_fmac_f32_dpp v205, v101, v137 row_shl:15 row_mask:0xf bank_mask:0xf
	v_fmac_f32_dpp v205, v83, v141 row_shl:1 row_mask:0xf bank_mask:0xf
	v_fmac_f32_dpp v205, v67, v141 row_shr:15 row_mask:0xf bank_mask:0xf
	v_pk_fma_f32 v[206:207], v[84:85], v[146:147], v[122:123]
	v_pk_fma_f32 v[200:201], v[86:87], v[156:157], v[128:129]
	v_fmac_f32_dpp v206, v84, v138 row_shr:1 row_mask:0xf bank_mask:0xf
	v_fmac_f32_dpp v206, v102, v138 row_shl:15 row_mask:0xf bank_mask:0xf
	v_fmac_f32_dpp v206, v84, v142 row_shl:1 row_mask:0xf bank_mask:0xf
	v_fmac_f32_dpp v206, v68, v142 row_shr:15 row_mask:0xf bank_mask:0xf
	v_fmac_f32_dpp v200, v86, v148 row_shr:1 row_mask:0xf bank_mask:0xf
	v_fmac_f32_dpp v200, v112, v148 row_shl:15 row_mask:0xf bank_mask:0xf
	v_fmac_f32_dpp v200, v86, v152 row_shl:1 row_mask:0xf bank_mask:0xf
	v_fmac_f32_dpp v200, v74, v152 row_shr:15 row_mask:0xf bank_mask:0xf
	v_fmac_f32_dpp v207, v85, v139 row_shr:1 row_mask:0xf bank_mask:0xf
	v_fmac_f32_dpp v207, v103, v139 row_shl:15 row_mask:0xf bank_mask:0xf
	v_fmac_f32_dpp v207, v85, v143 row_shl:1 row_mask:0xf bank_mask:0xf
	v_fmac_f32_dpp v207, v69, v143 row_shr:15 row_mask:0xf bank_mask:0xf
	v_fmac_f32_dpp v201, v87, v149 row_shr:1 row_mask:0xf bank_mask:0xf
	v_fmac_f32_dpp v201, v113, v149 row_shl:15 row_mask:0xf bank_mask:0xf
	v_fmac_f32_dpp v201, v87, v153 row_shl:1 row_mask:0xf bank_mask:0xf
	v_fmac_f32_dpp v201, v75, v153 row_shr:15 row_mask:0xf bank_mask:0xf
	v_pk_fma_f32 v[202:203], v[88:89], v[158:159], v[130:131]
	v_fmac_f32_dpp v202, v88, v150 row_shr:1 row_mask:0xf bank_mask:0xf
	v_fmac_f32_dpp v202, v114, v150 row_shl:15 row_mask:0xf bank_mask:0xf
	v_fmac_f32_dpp v202, v88, v154 row_shl:1 row_mask:0xf bank_mask:0xf
	v_fmac_f32_dpp v202, v76, v154 row_shr:15 row_mask:0xf bank_mask:0xf
	v_fmac_f32_dpp v203, v89, v151 row_shr:1 row_mask:0xf bank_mask:0xf
	v_fmac_f32_dpp v203, v115, v151 row_shl:15 row_mask:0xf bank_mask:0xf
	v_fmac_f32_dpp v203, v89, v155 row_shl:1 row_mask:0xf bank_mask:0xf
	v_fmac_f32_dpp v203, v77, v155 row_shr:15 row_mask:0xf bank_mask:0xf
	v_pk_mul_f32 v[246:247], v[200:201], s[100:101]
	v_pk_mul_f32 v[248:249], v[202:203], s[100:101]
	v_exp_f32_e32 v246, v246
	v_exp_f32_e32 v247, v247
	v_pk_mul_f32 v[224:225], v[204:205], s[100:101]
	v_exp_f32_e32 v248, v248
	v_exp_f32_e32 v249, v249
	v_pk_mul_f32 v[228:229], v[206:207], s[100:101]
	v_exp_f32_e32 v224, v224
	v_exp_f32_e32 v225, v225
	v_pk_add_f32 v[246:247], v[246:247], v[250:251]
	v_exp_f32_e32 v228, v228
	v_exp_f32_e32 v229, v229
	v_pk_add_f32 v[248:249], v[248:249], v[250:251]
	v_rcp_f32_e32 v246, v246
	v_rcp_f32_e32 v247, v247
	v_pk_add_f32 v[224:225], v[224:225], v[250:251]
	v_rcp_f32_e32 v248, v248
	v_rcp_f32_e32 v249, v249
	v_pk_add_f32 v[228:229], v[228:229], v[250:251]
	v_rcp_f32_e32 v224, v224
	v_rcp_f32_e32 v225, v225
	v_pk_mul_f32 v[246:247], v[200:201], v[246:247]
	v_rcp_f32_e32 v228, v228
	v_rcp_f32_e32 v229, v229
	v_pk_mul_f32 v[248:249], v[202:203], v[248:249]
	v_pk_mul_f32 v[246:247], v[94:95], v[246:247]
	v_pk_mul_f32 v[224:225], v[204:205], v[224:225]
	v_pk_mul_f32 v[248:249], v[96:97], v[248:249]
	s_nop 0
	v_pk_mul_f32 v[228:229], v[206:207], v[228:229]
	v_pk_mul_f32 v[224:225], v[90:91], v[224:225]
	v_pk_mul_f32 v[228:229], v[92:93], v[228:229]
	v_cvt_pk_bf16_f32 v90, v246, v247
	v_or_b32_e32 v94, 32, v240
	v_mad_i64_i32 v[94:95], s[4:5], v94, s79, v[132:133]
	v_lshl_add_u64 v[94:95], v[94:95], 0, v[134:135]
	v_cvt_pk_bf16_f32 v91, v248, v249
	v_cvt_pk_bf16_f32 v92, v224, v225
	v_cvt_pk_bf16_f32 v93, v228, v229
	global_store_dwordx4 v[94:95], v[90:93], off
	s_nop 1
	v_pk_fma_f32 v[200:201], v[74:75], v[156:157], v[128:129]
	s_nop 1
	v_fmac_f32_dpp v200, v74, v148 row_shr:1 row_mask:0xf bank_mask:0xf
	v_fmac_f32_dpp v200, v86, v148 row_shl:15 row_mask:0xf bank_mask:0xf
	v_fmac_f32_dpp v200, v74, v152 row_shl:1 row_mask:0xf bank_mask:0xf
	v_fmac_f32_dpp v200, v184, v152 row_shr:15 row_mask:0xf bank_mask:0xf
	v_fmac_f32_dpp v201, v75, v149 row_shr:1 row_mask:0xf bank_mask:0xf
	v_fmac_f32_dpp v201, v87, v149 row_shl:15 row_mask:0xf bank_mask:0xf
	v_fmac_f32_dpp v201, v75, v153 row_shl:1 row_mask:0xf bank_mask:0xf
	v_fmac_f32_dpp v201, v185, v153 row_shr:15 row_mask:0xf bank_mask:0xf
	v_pk_fma_f32 v[202:203], v[76:77], v[158:159], v[130:131]
	v_fmac_f32_dpp v202, v76, v150 row_shr:1 row_mask:0xf bank_mask:0xf
	v_fmac_f32_dpp v202, v88, v150 row_shl:15 row_mask:0xf bank_mask:0xf
	v_fmac_f32_dpp v202, v76, v154 row_shl:1 row_mask:0xf bank_mask:0xf
	v_fmac_f32_dpp v202, v186, v154 row_shr:15 row_mask:0xf bank_mask:0xf
	v_fmac_f32_dpp v203, v77, v151 row_shr:1 row_mask:0xf bank_mask:0xf
	v_fmac_f32_dpp v203, v89, v151 row_shl:15 row_mask:0xf bank_mask:0xf
	v_fmac_f32_dpp v203, v77, v155 row_shl:1 row_mask:0xf bank_mask:0xf
	v_fmac_f32_dpp v203, v187, v155 row_shr:15 row_mask:0xf bank_mask:0xf
	v_pk_fma_f32 v[204:205], v[66:67], v[144:145], v[120:121]
	s_waitcnt lgkmcnt(2)
	v_fmac_f32_dpp v204, v66, v136 row_shr:1 row_mask:0xf bank_mask:0xf
	v_fmac_f32_dpp v204, v82, v136 row_shl:15 row_mask:0xf bank_mask:0xf
	v_fmac_f32_dpp v204, v66, v140 row_shl:1 row_mask:0xf bank_mask:0xf
	v_fmac_f32_dpp v204, v180, v140 row_shr:15 row_mask:0xf bank_mask:0xf
	v_fmac_f32_dpp v205, v67, v137 row_shr:1 row_mask:0xf bank_mask:0xf
	v_fmac_f32_dpp v205, v83, v137 row_shl:15 row_mask:0xf bank_mask:0xf
	v_fmac_f32_dpp v205, v67, v141 row_shl:1 row_mask:0xf bank_mask:0xf
	v_fmac_f32_dpp v205, v181, v141 row_shr:15 row_mask:0xf bank_mask:0xf
	v_pk_fma_f32 v[206:207], v[68:69], v[146:147], v[122:123]
	v_fmac_f32_dpp v206, v68, v138 row_shr:1 row_mask:0xf bank_mask:0xf
	v_fmac_f32_dpp v206, v84, v138 row_shl:15 row_mask:0xf bank_mask:0xf
	v_fmac_f32_dpp v206, v68, v142 row_shl:1 row_mask:0xf bank_mask:0xf
	v_fmac_f32_dpp v206, v182, v142 row_shr:15 row_mask:0xf bank_mask:0xf
	v_fmac_f32_dpp v207, v69, v139 row_shr:1 row_mask:0xf bank_mask:0xf
	v_fmac_f32_dpp v207, v85, v139 row_shl:15 row_mask:0xf bank_mask:0xf
	v_fmac_f32_dpp v207, v69, v143 row_shl:1 row_mask:0xf bank_mask:0xf
	v_fmac_f32_dpp v207, v183, v143 row_shr:15 row_mask:0xf bank_mask:0xf
	v_pk_mul_f32 v[246:247], v[200:201], s[100:101]
	v_pk_mul_f32 v[248:249], v[202:203], s[100:101]
	v_exp_f32_e32 v246, v246
	v_exp_f32_e32 v247, v247
	v_pk_mul_f32 v[224:225], v[204:205], s[100:101]
	v_exp_f32_e32 v248, v248
	v_exp_f32_e32 v249, v249
	v_pk_mul_f32 v[228:229], v[206:207], s[100:101]
	v_exp_f32_e32 v224, v224
	v_exp_f32_e32 v225, v225
	v_pk_add_f32 v[246:247], v[246:247], v[250:251]
	v_exp_f32_e32 v228, v228
	v_exp_f32_e32 v229, v229
	v_pk_add_f32 v[248:249], v[248:249], v[250:251]
	v_rcp_f32_e32 v246, v246
	v_rcp_f32_e32 v247, v247
	v_pk_add_f32 v[224:225], v[224:225], v[250:251]
	v_rcp_f32_e32 v248, v248
	v_rcp_f32_e32 v249, v249
	v_pk_add_f32 v[228:229], v[228:229], v[250:251]
	v_rcp_f32_e32 v224, v224
	v_rcp_f32_e32 v225, v225
	v_pk_mul_f32 v[246:247], v[200:201], v[246:247]
	v_rcp_f32_e32 v228, v228
	v_rcp_f32_e32 v229, v229
	v_pk_mul_f32 v[248:249], v[202:203], v[248:249]
	v_pk_mul_f32 v[246:247], v[78:79], v[246:247]
	v_pk_mul_f32 v[224:225], v[204:205], v[224:225]
	v_pk_mul_f32 v[248:249], v[80:81], v[248:249]
	s_nop 0
	v_pk_mul_f32 v[228:229], v[206:207], v[228:229]
	v_pk_mul_f32 v[224:225], v[70:71], v[224:225]
	v_pk_mul_f32 v[228:229], v[72:73], v[228:229]
	v_cvt_pk_bf16_f32 v66, v246, v247
	v_cvt_pk_bf16_f32 v67, v248, v249
	v_cvt_pk_bf16_f32 v68, v224, v225
	v_or_b32_e32 v70, 48, v240
	v_mad_i64_i32 v[70:71], s[4:5], v70, s79, v[132:133]
	v_lshl_add_u64 v[70:71], v[70:71], 0, v[134:135]
	v_cvt_pk_bf16_f32 v69, v228, v229
	global_store_dwordx4 v[70:71], v[66:69], off
	v_pk_fma_f32 v[202:203], v[56:57], v[158:159], v[130:131]
	s_waitcnt lgkmcnt(1)
	v_fmac_f32_dpp v203, v57, v151 row_shr:1 row_mask:0xf bank_mask:0xf
	v_fmac_f32_dpp v203, v179, v151 row_shl:15 row_mask:0xf bank_mask:0xf
	v_fmac_f32_dpp v203, v57, v155 row_shl:1 row_mask:0xf bank_mask:0xf
	v_fmac_f32_dpp v203, v41, v155 row_shr:15 row_mask:0xf bank_mask:0xf
	v_pk_fma_f32 v[204:205], v[50:51], v[144:145], v[120:121]
	v_pk_fma_f32 v[200:201], v[54:55], v[156:157], v[128:129]
	s_nop 1
	v_fmac_f32_dpp v200, v54, v148 row_shr:1 row_mask:0xf bank_mask:0xf
	v_fmac_f32_dpp v200, v176, v148 row_shl:15 row_mask:0xf bank_mask:0xf
	v_fmac_f32_dpp v200, v54, v152 row_shl:1 row_mask:0xf bank_mask:0xf
	v_fmac_f32_dpp v200, v38, v152 row_shr:15 row_mask:0xf bank_mask:0xf
	v_fmac_f32_dpp v201, v55, v149 row_shr:1 row_mask:0xf bank_mask:0xf
	v_fmac_f32_dpp v201, v177, v149 row_shl:15 row_mask:0xf bank_mask:0xf
	v_fmac_f32_dpp v201, v55, v153 row_shl:1 row_mask:0xf bank_mask:0xf
	v_fmac_f32_dpp v201, v39, v153 row_shr:15 row_mask:0xf bank_mask:0xf
	v_fmac_f32_dpp v202, v56, v150 row_shr:1 row_mask:0xf bank_mask:0xf
	v_fmac_f32_dpp v202, v178, v150 row_shl:15 row_mask:0xf bank_mask:0xf
	v_fmac_f32_dpp v202, v56, v154 row_shl:1 row_mask:0xf bank_mask:0xf
	v_fmac_f32_dpp v202, v40, v154 row_shr:15 row_mask:0xf bank_mask:0xf
	s_waitcnt lgkmcnt(0)
	v_fmac_f32_dpp v204, v50, v136 row_shr:1 row_mask:0xf bank_mask:0xf
	v_fmac_f32_dpp v204, v172, v136 row_shl:15 row_mask:0xf bank_mask:0xf
	v_fmac_f32_dpp v204, v50, v140 row_shl:1 row_mask:0xf bank_mask:0xf
	v_fmac_f32_dpp v204, v34, v140 row_shr:15 row_mask:0xf bank_mask:0xf
	v_fmac_f32_dpp v205, v51, v137 row_shr:1 row_mask:0xf bank_mask:0xf
	v_fmac_f32_dpp v205, v173, v137 row_shl:15 row_mask:0xf bank_mask:0xf
	v_fmac_f32_dpp v205, v51, v141 row_shl:1 row_mask:0xf bank_mask:0xf
	v_fmac_f32_dpp v205, v35, v141 row_shr:15 row_mask:0xf bank_mask:0xf
	v_pk_fma_f32 v[206:207], v[52:53], v[146:147], v[122:123]
	v_fmac_f32_dpp v206, v52, v138 row_shr:1 row_mask:0xf bank_mask:0xf
	v_fmac_f32_dpp v206, v174, v138 row_shl:15 row_mask:0xf bank_mask:0xf
	v_fmac_f32_dpp v206, v52, v142 row_shl:1 row_mask:0xf bank_mask:0xf
	v_fmac_f32_dpp v206, v36, v142 row_shr:15 row_mask:0xf bank_mask:0xf
	v_fmac_f32_dpp v207, v53, v139 row_shr:1 row_mask:0xf bank_mask:0xf
	v_fmac_f32_dpp v207, v175, v139 row_shl:15 row_mask:0xf bank_mask:0xf
	v_fmac_f32_dpp v207, v53, v143 row_shl:1 row_mask:0xf bank_mask:0xf
	v_fmac_f32_dpp v207, v37, v143 row_shr:15 row_mask:0xf bank_mask:0xf
	v_pk_mul_f32 v[246:247], v[200:201], s[100:101]
	v_pk_mul_f32 v[248:249], v[202:203], s[100:101]
	v_exp_f32_e32 v246, v246
	v_exp_f32_e32 v247, v247
	v_pk_mul_f32 v[224:225], v[204:205], s[100:101]
	v_exp_f32_e32 v248, v248
	v_exp_f32_e32 v249, v249
	v_pk_mul_f32 v[228:229], v[206:207], s[100:101]
	v_exp_f32_e32 v224, v224
	v_exp_f32_e32 v225, v225
	v_pk_add_f32 v[246:247], v[246:247], v[250:251]
	v_exp_f32_e32 v228, v228
	v_exp_f32_e32 v229, v229
	v_pk_add_f32 v[248:249], v[248:249], v[250:251]
	v_rcp_f32_e32 v246, v246
	v_rcp_f32_e32 v247, v247
	v_pk_add_f32 v[224:225], v[224:225], v[250:251]
	v_rcp_f32_e32 v248, v248
	v_rcp_f32_e32 v249, v249
	v_pk_add_f32 v[228:229], v[228:229], v[250:251]
	v_rcp_f32_e32 v224, v224
	v_rcp_f32_e32 v225, v225
	v_pk_mul_f32 v[246:247], v[200:201], v[246:247]
	v_rcp_f32_e32 v228, v228
	v_rcp_f32_e32 v229, v229
	v_pk_mul_f32 v[248:249], v[202:203], v[248:249]
	v_pk_mul_f32 v[246:247], v[62:63], v[246:247]
	v_pk_mul_f32 v[224:225], v[204:205], v[224:225]
	v_pk_mul_f32 v[248:249], v[64:65], v[248:249]
	s_nop 0
	v_pk_mul_f32 v[228:229], v[206:207], v[228:229]
	v_pk_mul_f32 v[224:225], v[58:59], v[224:225]
	v_pk_mul_f32 v[228:229], v[60:61], v[228:229]
	v_add_u32_e32 v66, 0x80, v240
	v_cvt_pk_bf16_f32 v58, v246, v247
	v_mad_i64_i32 v[62:63], s[4:5], v66, s79, v[132:133]
	v_lshl_add_u64 v[62:63], v[62:63], 0, v[134:135]
	v_cvt_pk_bf16_f32 v59, v248, v249
	v_cvt_pk_bf16_f32 v60, v224, v225
	v_cvt_pk_bf16_f32 v61, v228, v229
	global_store_dwordx4 v[62:63], v[58:61], off
	s_nop 1
	v_pk_fma_f32 v[200:201], v[38:39], v[156:157], v[128:129]
	v_fmac_f32_dpp v200, v38, v148 row_shr:1 row_mask:0xf bank_mask:0xf
	v_fmac_f32_dpp v200, v54, v148 row_shl:15 row_mask:0xf bank_mask:0xf
	v_fmac_f32_dpp v200, v38, v152 row_shl:1 row_mask:0xf bank_mask:0xf
	v_fmac_f32_dpp v200, v22, v152 row_shr:15 row_mask:0xf bank_mask:0xf
	v_fmac_f32_dpp v201, v39, v149 row_shr:1 row_mask:0xf bank_mask:0xf
	v_fmac_f32_dpp v201, v55, v149 row_shl:15 row_mask:0xf bank_mask:0xf
	v_fmac_f32_dpp v201, v39, v153 row_shl:1 row_mask:0xf bank_mask:0xf
	v_fmac_f32_dpp v201, v23, v153 row_shr:15 row_mask:0xf bank_mask:0xf
	v_pk_fma_f32 v[202:203], v[40:41], v[158:159], v[130:131]
	v_fmac_f32_dpp v202, v40, v150 row_shr:1 row_mask:0xf bank_mask:0xf
	v_fmac_f32_dpp v202, v56, v150 row_shl:15 row_mask:0xf bank_mask:0xf
	v_fmac_f32_dpp v202, v40, v154 row_shl:1 row_mask:0xf bank_mask:0xf
	v_fmac_f32_dpp v202, v24, v154 row_shr:15 row_mask:0xf bank_mask:0xf
	v_fmac_f32_dpp v203, v41, v151 row_shr:1 row_mask:0xf bank_mask:0xf
	v_fmac_f32_dpp v203, v57, v151 row_shl:15 row_mask:0xf bank_mask:0xf
	v_fmac_f32_dpp v203, v41, v155 row_shl:1 row_mask:0xf bank_mask:0xf
	v_fmac_f32_dpp v203, v25, v155 row_shr:15 row_mask:0xf bank_mask:0xf
	v_pk_fma_f32 v[204:205], v[34:35], v[144:145], v[120:121]
	v_fmac_f32_dpp v204, v34, v136 row_shr:1 row_mask:0xf bank_mask:0xf
	v_fmac_f32_dpp v204, v50, v136 row_shl:15 row_mask:0xf bank_mask:0xf
	v_fmac_f32_dpp v204, v34, v140 row_shl:1 row_mask:0xf bank_mask:0xf
	v_fmac_f32_dpp v204, v18, v140 row_shr:15 row_mask:0xf bank_mask:0xf
	v_fmac_f32_dpp v205, v35, v137 row_shr:1 row_mask:0xf bank_mask:0xf
	v_fmac_f32_dpp v205, v51, v137 row_shl:15 row_mask:0xf bank_mask:0xf
	v_fmac_f32_dpp v205, v35, v141 row_shl:1 row_mask:0xf bank_mask:0xf
	v_fmac_f32_dpp v205, v19, v141 row_shr:15 row_mask:0xf bank_mask:0xf
	v_pk_fma_f32 v[206:207], v[36:37], v[146:147], v[122:123]
	v_fmac_f32_dpp v206, v36, v138 row_shr:1 row_mask:0xf bank_mask:0xf
	v_fmac_f32_dpp v206, v52, v138 row_shl:15 row_mask:0xf bank_mask:0xf
	v_fmac_f32_dpp v206, v36, v142 row_shl:1 row_mask:0xf bank_mask:0xf
	v_fmac_f32_dpp v206, v20, v142 row_shr:15 row_mask:0xf bank_mask:0xf
	v_fmac_f32_dpp v207, v37, v139 row_shr:1 row_mask:0xf bank_mask:0xf
	v_fmac_f32_dpp v207, v53, v139 row_shl:15 row_mask:0xf bank_mask:0xf
	v_fmac_f32_dpp v207, v37, v143 row_shl:1 row_mask:0xf bank_mask:0xf
	v_fmac_f32_dpp v207, v21, v143 row_shr:15 row_mask:0xf bank_mask:0xf
	v_pk_mul_f32 v[246:247], v[200:201], s[100:101]
	v_pk_mul_f32 v[248:249], v[202:203], s[100:101]
	v_exp_f32_e32 v246, v246
	v_exp_f32_e32 v247, v247
	v_pk_mul_f32 v[224:225], v[204:205], s[100:101]
	v_exp_f32_e32 v248, v248
	v_exp_f32_e32 v249, v249
	v_pk_mul_f32 v[228:229], v[206:207], s[100:101]
	v_exp_f32_e32 v224, v224
	v_exp_f32_e32 v225, v225
	v_pk_add_f32 v[246:247], v[246:247], v[250:251]
	v_exp_f32_e32 v228, v228
	v_exp_f32_e32 v229, v229
	v_pk_add_f32 v[248:249], v[248:249], v[250:251]
	v_rcp_f32_e32 v246, v246
	v_rcp_f32_e32 v247, v247
	v_pk_add_f32 v[224:225], v[224:225], v[250:251]
	v_rcp_f32_e32 v248, v248
	v_rcp_f32_e32 v249, v249
	v_pk_add_f32 v[228:229], v[228:229], v[250:251]
	v_rcp_f32_e32 v224, v224
	v_rcp_f32_e32 v225, v225
	v_pk_mul_f32 v[246:247], v[200:201], v[246:247]
	v_rcp_f32_e32 v228, v228
	v_rcp_f32_e32 v229, v229
	v_pk_mul_f32 v[248:249], v[202:203], v[248:249]
	v_pk_mul_f32 v[246:247], v[46:47], v[246:247]
	v_pk_mul_f32 v[224:225], v[204:205], v[224:225]
	v_pk_mul_f32 v[248:249], v[48:49], v[248:249]
	s_nop 0
	v_pk_mul_f32 v[228:229], v[206:207], v[228:229]
	v_pk_mul_f32 v[224:225], v[42:43], v[224:225]
	v_pk_mul_f32 v[228:229], v[44:45], v[228:229]
	v_cvt_pk_bf16_f32 v42, v246, v247
	v_add_u32_e32 v46, 0x90, v240
	v_mad_i64_i32 v[46:47], s[4:5], v46, s79, v[132:133]
	v_lshl_add_u64 v[46:47], v[46:47], 0, v[134:135]
	v_cvt_pk_bf16_f32 v43, v248, v249
	v_cvt_pk_bf16_f32 v44, v224, v225
	v_cvt_pk_bf16_f32 v45, v228, v229
	global_store_dwordx4 v[46:47], v[42:45], off
	s_nop 1
	v_pk_fma_f32 v[200:201], v[22:23], v[156:157], v[128:129]
	v_fmac_f32_dpp v200, v22, v148 row_shr:1 row_mask:0xf bank_mask:0xf
	v_fmac_f32_dpp v200, v38, v148 row_shl:15 row_mask:0xf bank_mask:0xf
	v_fmac_f32_dpp v200, v22, v152 row_shl:1 row_mask:0xf bank_mask:0xf
	v_fmac_f32_dpp v200, v14, v152 row_shr:15 row_mask:0xf bank_mask:0xf
	v_fmac_f32_dpp v201, v23, v149 row_shr:1 row_mask:0xf bank_mask:0xf
	v_fmac_f32_dpp v201, v39, v149 row_shl:15 row_mask:0xf bank_mask:0xf
	v_fmac_f32_dpp v201, v23, v153 row_shl:1 row_mask:0xf bank_mask:0xf
	v_fmac_f32_dpp v201, v15, v153 row_shr:15 row_mask:0xf bank_mask:0xf
	v_pk_fma_f32 v[202:203], v[24:25], v[158:159], v[130:131]
	v_fmac_f32_dpp v202, v24, v150 row_shr:1 row_mask:0xf bank_mask:0xf
	v_fmac_f32_dpp v202, v40, v150 row_shl:15 row_mask:0xf bank_mask:0xf
	v_fmac_f32_dpp v202, v24, v154 row_shl:1 row_mask:0xf bank_mask:0xf
	v_fmac_f32_dpp v202, v16, v154 row_shr:15 row_mask:0xf bank_mask:0xf
	v_fmac_f32_dpp v203, v25, v151 row_shr:1 row_mask:0xf bank_mask:0xf
	v_fmac_f32_dpp v203, v41, v151 row_shl:15 row_mask:0xf bank_mask:0xf
	v_fmac_f32_dpp v203, v25, v155 row_shl:1 row_mask:0xf bank_mask:0xf
	v_fmac_f32_dpp v203, v17, v155 row_shr:15 row_mask:0xf bank_mask:0xf
	v_pk_fma_f32 v[204:205], v[18:19], v[144:145], v[120:121]
	v_fmac_f32_dpp v204, v18, v136 row_shr:1 row_mask:0xf bank_mask:0xf
	v_fmac_f32_dpp v204, v34, v136 row_shl:15 row_mask:0xf bank_mask:0xf
	v_fmac_f32_dpp v204, v18, v140 row_shl:1 row_mask:0xf bank_mask:0xf
	v_fmac_f32_dpp v204, v10, v140 row_shr:15 row_mask:0xf bank_mask:0xf
	v_fmac_f32_dpp v205, v19, v137 row_shr:1 row_mask:0xf bank_mask:0xf
	v_fmac_f32_dpp v205, v35, v137 row_shl:15 row_mask:0xf bank_mask:0xf
	v_fmac_f32_dpp v205, v19, v141 row_shl:1 row_mask:0xf bank_mask:0xf
	v_fmac_f32_dpp v205, v11, v141 row_shr:15 row_mask:0xf bank_mask:0xf
	v_pk_fma_f32 v[206:207], v[20:21], v[146:147], v[122:123]
	v_fmac_f32_dpp v206, v20, v138 row_shr:1 row_mask:0xf bank_mask:0xf
	v_fmac_f32_dpp v206, v36, v138 row_shl:15 row_mask:0xf bank_mask:0xf
	v_fmac_f32_dpp v206, v20, v142 row_shl:1 row_mask:0xf bank_mask:0xf
	v_fmac_f32_dpp v206, v12, v142 row_shr:15 row_mask:0xf bank_mask:0xf
	v_fmac_f32_dpp v207, v21, v139 row_shr:1 row_mask:0xf bank_mask:0xf
	v_fmac_f32_dpp v207, v37, v139 row_shl:15 row_mask:0xf bank_mask:0xf
	v_fmac_f32_dpp v207, v21, v143 row_shl:1 row_mask:0xf bank_mask:0xf
	v_fmac_f32_dpp v207, v13, v143 row_shr:15 row_mask:0xf bank_mask:0xf
	v_pk_mul_f32 v[246:247], v[200:201], s[100:101]
	v_pk_mul_f32 v[248:249], v[202:203], s[100:101]
	v_exp_f32_e32 v246, v246
	v_exp_f32_e32 v247, v247
	v_pk_mul_f32 v[224:225], v[204:205], s[100:101]
	v_exp_f32_e32 v248, v248
	v_exp_f32_e32 v249, v249
	v_pk_mul_f32 v[228:229], v[206:207], s[100:101]
	v_exp_f32_e32 v224, v224
	v_exp_f32_e32 v225, v225
	v_pk_add_f32 v[246:247], v[246:247], v[250:251]
	v_exp_f32_e32 v228, v228
	v_exp_f32_e32 v229, v229
	v_pk_add_f32 v[248:249], v[248:249], v[250:251]
	v_rcp_f32_e32 v246, v246
	v_rcp_f32_e32 v247, v247
	v_pk_add_f32 v[224:225], v[224:225], v[250:251]
	v_rcp_f32_e32 v248, v248
	v_rcp_f32_e32 v249, v249
	v_pk_add_f32 v[228:229], v[228:229], v[250:251]
	v_rcp_f32_e32 v224, v224
	v_rcp_f32_e32 v225, v225
	v_pk_mul_f32 v[246:247], v[200:201], v[246:247]
	v_rcp_f32_e32 v228, v228
	v_rcp_f32_e32 v229, v229
	v_pk_mul_f32 v[248:249], v[202:203], v[248:249]
	v_pk_mul_f32 v[246:247], v[30:31], v[246:247]
	v_pk_mul_f32 v[224:225], v[204:205], v[224:225]
	v_pk_mul_f32 v[248:249], v[32:33], v[248:249]
	s_nop 0
	v_pk_mul_f32 v[228:229], v[206:207], v[228:229]
	v_pk_mul_f32 v[224:225], v[26:27], v[224:225]
	v_pk_mul_f32 v[228:229], v[28:29], v[228:229]
	v_cvt_pk_bf16_f32 v26, v246, v247
	v_add_u32_e32 v30, 0xa0, v240
	v_mad_i64_i32 v[30:31], s[4:5], v30, s79, v[132:133]
	v_lshl_add_u64 v[30:31], v[30:31], 0, v[134:135]
	v_cvt_pk_bf16_f32 v27, v248, v249
	v_cvt_pk_bf16_f32 v28, v224, v225
	v_cvt_pk_bf16_f32 v29, v228, v229
	global_store_dwordx4 v[30:31], v[26:29], off
	v_pk_fma_f32 v[206:207], v[12:13], v[146:147], v[122:123]
	v_pk_fma_f32 v[202:203], v[16:17], v[158:159], v[130:131]
	v_pk_fma_f32 v[200:201], v[14:15], v[156:157], v[128:129]
	s_nop 1
	v_fmac_f32_dpp v200, v14, v148 row_shr:1 row_mask:0xf bank_mask:0xf
	v_fmac_f32_dpp v200, v22, v148 row_shl:15 row_mask:0xf bank_mask:0xf
	v_fmac_f32_dpp v200, v14, v152 row_shl:1 row_mask:0xf bank_mask:0xf
	v_fmac_f32_dpp v200, v168, v152 row_shr:15 row_mask:0xf bank_mask:0xf
	v_fmac_f32_dpp v201, v15, v149 row_shr:1 row_mask:0xf bank_mask:0xf
	v_fmac_f32_dpp v201, v23, v149 row_shl:15 row_mask:0xf bank_mask:0xf
	v_fmac_f32_dpp v201, v15, v153 row_shl:1 row_mask:0xf bank_mask:0xf
	v_fmac_f32_dpp v201, v169, v153 row_shr:15 row_mask:0xf bank_mask:0xf
	v_fmac_f32_dpp v202, v16, v150 row_shr:1 row_mask:0xf bank_mask:0xf
	v_fmac_f32_dpp v202, v24, v150 row_shl:15 row_mask:0xf bank_mask:0xf
	v_fmac_f32_dpp v202, v16, v154 row_shl:1 row_mask:0xf bank_mask:0xf
	v_fmac_f32_dpp v202, v170, v154 row_shr:15 row_mask:0xf bank_mask:0xf
	v_pk_fma_f32 v[204:205], v[10:11], v[144:145], v[120:121]
	v_fmac_f32_dpp v204, v10, v136 row_shr:1 row_mask:0xf bank_mask:0xf
	v_fmac_f32_dpp v204, v18, v136 row_shl:15 row_mask:0xf bank_mask:0xf
	v_fmac_f32_dpp v204, v10, v140 row_shl:1 row_mask:0xf bank_mask:0xf
	v_fmac_f32_dpp v204, v164, v140 row_shr:15 row_mask:0xf bank_mask:0xf
	v_fmac_f32_dpp v205, v11, v137 row_shr:1 row_mask:0xf bank_mask:0xf
	v_fmac_f32_dpp v205, v19, v137 row_shl:15 row_mask:0xf bank_mask:0xf
	v_fmac_f32_dpp v205, v11, v141 row_shl:1 row_mask:0xf bank_mask:0xf
	v_fmac_f32_dpp v205, v165, v141 row_shr:15 row_mask:0xf bank_mask:0xf
	v_fmac_f32_dpp v206, v12, v138 row_shr:1 row_mask:0xf bank_mask:0xf
	v_fmac_f32_dpp v206, v20, v138 row_shl:15 row_mask:0xf bank_mask:0xf
	v_fmac_f32_dpp v206, v12, v142 row_shl:1 row_mask:0xf bank_mask:0xf
	v_fmac_f32_dpp v206, v166, v142 row_shr:15 row_mask:0xf bank_mask:0xf
	v_fmac_f32_dpp v207, v13, v139 row_shr:1 row_mask:0xf bank_mask:0xf
	v_fmac_f32_dpp v207, v21, v139 row_shl:15 row_mask:0xf bank_mask:0xf
	v_fmac_f32_dpp v207, v13, v143 row_shl:1 row_mask:0xf bank_mask:0xf
	v_fmac_f32_dpp v207, v167, v143 row_shr:15 row_mask:0xf bank_mask:0xf
	v_fmac_f32_dpp v203, v17, v151 row_shr:1 row_mask:0xf bank_mask:0xf
	v_fmac_f32_dpp v203, v25, v151 row_shl:15 row_mask:0xf bank_mask:0xf
	v_fmac_f32_dpp v203, v17, v155 row_shl:1 row_mask:0xf bank_mask:0xf
	v_fmac_f32_dpp v203, v171, v155 row_shr:15 row_mask:0xf bank_mask:0xf
	v_pk_mul_f32 v[246:247], v[200:201], s[100:101]
	v_pk_mul_f32 v[248:249], v[202:203], s[100:101]
	v_exp_f32_e32 v246, v246
	v_exp_f32_e32 v247, v247
	v_pk_mul_f32 v[224:225], v[204:205], s[100:101]
	v_exp_f32_e32 v248, v248
	v_exp_f32_e32 v249, v249
	v_pk_mul_f32 v[228:229], v[206:207], s[100:101]
	v_exp_f32_e32 v224, v224
	v_exp_f32_e32 v225, v225
	v_pk_add_f32 v[246:247], v[246:247], v[250:251]
	v_exp_f32_e32 v228, v228
	v_exp_f32_e32 v229, v229
	v_pk_add_f32 v[248:249], v[248:249], v[250:251]
	v_rcp_f32_e32 v246, v246
	v_rcp_f32_e32 v247, v247
	v_pk_add_f32 v[224:225], v[224:225], v[250:251]
	v_rcp_f32_e32 v248, v248
	v_rcp_f32_e32 v249, v249
	v_pk_add_f32 v[228:229], v[228:229], v[250:251]
	v_rcp_f32_e32 v224, v224
	v_rcp_f32_e32 v225, v225
	v_pk_mul_f32 v[246:247], v[200:201], v[246:247]
	v_rcp_f32_e32 v228, v228
	v_rcp_f32_e32 v229, v229
	v_pk_mul_f32 v[248:249], v[202:203], v[248:249]
	v_pk_mul_f32 v[246:247], v[6:7], v[246:247]
	v_pk_mul_f32 v[224:225], v[204:205], v[224:225]
	v_pk_mul_f32 v[248:249], v[8:9], v[248:249]
	s_nop 0
	v_pk_mul_f32 v[228:229], v[206:207], v[228:229]
	v_pk_mul_f32 v[224:225], v[2:3], v[224:225]
	v_pk_mul_f32 v[228:229], v[4:5], v[228:229]
	v_cvt_pk_bf16_f32 v2, v246, v247
	v_add_u32_e32 v6, 0xb0, v240
	v_mad_i64_i32 v[6:7], s[4:5], v6, s79, v[132:133]
	v_lshl_add_u64 v[6:7], v[6:7], 0, v[134:135]
	s_mov_b64 s[4:5], -1
	v_cvt_pk_bf16_f32 v3, v248, v249
	v_cvt_pk_bf16_f32 v4, v224, v225
	v_cvt_pk_bf16_f32 v5, v228, v229
	global_store_dwordx4 v[6:7], v[2:5], off
	s_cbranch_vccnz .LBB0_972
	s_and_b64 vcc, exec, s[46:47]
	s_cbranch_vccnz .LBB0_971
	s_barrier
	s_branch .LBB0_971
